# speedup vs baseline: 1.0183x; 1.0081x over previous
; #define SBAR() __builtin_amdgcn_sched_barrier(0)
; __device__ __forceinline__ void finishSM(f32x16& p0, f32x16& p1, float alpha, float& l_reg, bf16x8& pa0, bf16x8& pa1, bf16x8& pa2, bf16x8& pa3) {
; #pragma unroll
;   for (int r = 0; r < 16; ++r) p1[r] = __builtin_amdgcn_exp2f(p1[r]);
;   float ps = 0;
; #pragma unroll
;   for (int r = 0; r < 16; ++r) ps += p0[r];
; #pragma unroll
;   for (int r = 0; r < 16; ++r) ps += p1[r];
;   { auto rr = __builtin_amdgcn_permlane32_swap(__float_as_uint(ps), __float_as_uint(ps), false, false);
;     ps = __uint_as_float(rr[0]) + __uint_as_float(rr[1]); }
;   l_reg = l_reg * alpha + ps;
; __device__ __forceinline__ void attn_mla_dma(const bf16_t* __restrict__ Qb, const bf16_t* __restrict__ Kh, const bf16_t* __restrict__ Vh, bf16_t* __restrict__ Ob,
;                                              int seq, char* lds, const int tid) {
;     ...
;     SBAR(); qkt_mla<(int)SHM_K192>(pB0, pB1, ka, qr, qlds);
;     finishSM(pA0, pA1, alA, l_reg, pa0, pa1, pa2, pa3); SBAR();
;     DMA_TILE((j + 1) * KVBLK, 0, vnxt); SBAR();
;     pv_d0_t(o, vb0 + vprev * SHM_VV, pa0, pa1, pa2, pa3); partialSM<MLA>(pB0, pB1, m_reg, mnB, alB);
.LBB0_115:
	s_mov_b32 s55, s43
	s_mov_b32 s43, s52
	ds_read_b128 v[64:67], v169 offset:24576
	ds_read_b128 v[68:71], v169 offset:36864
	ds_read_b128 v[214:217], v190 offset:24576
	ds_read_b128 v[218:221], v190 offset:36864
	s_waitcnt lgkmcnt(0)
	v_mfma_f32_32x32x16_bf16 v[80:95], v[64:67], v[140:143], v[226:241]
	v_add_f32_e32 v144, v200, v145
	v_mfma_f32_32x32x16_bf16 v[64:79], v[68:71], v[140:143], v[226:241]
	v_add_f32_e32 v243, v203, v210
	v_add_f32_e32 v244, v202, v208
	v_add_f32_e32 v245, v205, v212
	v_add_f32_e32 v246, v199, v211
	v_add_f32_e32 v247, v201, v213
	v_mfma_f32_32x32x16_bf16 v[80:95], v[214:217], v[136:139], v[80:95]
	v_add_f32_e32 v251, v204, v207
	v_add_f32_e32 v252, v206, v209
	v_mov_b32_e32 v196, v158
	v_add_f32_e32 v144, v172, v144
	v_add_f32_e32 v243, v173, v243
	v_mfma_f32_32x32x16_bf16 v[64:79], v[218:221], v[136:139], v[64:79]
	ds_read_b128 v[214:217], v193 offset:24576
	ds_read_b128 v[218:221], v193 offset:36864
	v_add_f32_e32 v244, v170, v244
	v_add_f32_e32 v245, v171, v245
	v_add_f32_e32 v246, v196, v246
	v_mov_b32_e32 v222, v147
	v_mov_b32_e32 v223, v154
	v_mov_b32_e32 v224, v155
	s_waitcnt lgkmcnt(0)
	v_mfma_f32_32x32x16_bf16 v[80:95], v[214:217], v[132:135], v[80:95]
	v_mfma_f32_32x32x16_bf16 v[64:79], v[218:221], v[132:135], v[64:79]
	ds_read_b128 v[214:217], v192 offset:24576
	ds_read_b128 v[218:221], v192 offset:36864
	s_waitcnt lgkmcnt(0)
	v_mfma_f32_32x32x16_bf16 v[80:95], v[214:217], v[128:131], v[80:95]
	v_mfma_f32_32x32x16_bf16 v[64:79], v[218:221], v[128:131], v[64:79]
	ds_read_b128 v[214:217], v169 offset:24704
	ds_read_b128 v[218:221], v169 offset:36992
	s_waitcnt lgkmcnt(0)
	v_mfma_f32_32x32x16_bf16 v[80:95], v[214:217], v[124:127], v[80:95]
	v_mfma_f32_32x32x16_bf16 v[64:79], v[218:221], v[124:127], v[64:79]
	ds_read_b128 v[214:217], v190 offset:24704
	ds_read_b128 v[218:221], v190 offset:36992
	s_waitcnt lgkmcnt(0)
	v_mfma_f32_32x32x16_bf16 v[80:95], v[214:217], v[120:123], v[80:95]
	v_mfma_f32_32x32x16_bf16 v[64:79], v[218:221], v[120:123], v[64:79]
	ds_read_b128 v[214:217], v193 offset:24704
	ds_read_b128 v[218:221], v193 offset:36992
	s_waitcnt lgkmcnt(0)
	v_mfma_f32_32x32x16_bf16 v[80:95], v[214:217], v[116:119], v[80:95]
	v_mfma_f32_32x32x16_bf16 v[64:79], v[218:221], v[116:119], v[64:79]
	ds_read_b128 v[214:217], v192 offset:24704
	ds_read_b128 v[218:221], v192 offset:36992
	s_waitcnt lgkmcnt(0)
	v_mfma_f32_32x32x16_bf16 v[80:95], v[214:217], v[112:115], v[80:95]
	v_mfma_f32_32x32x16_bf16 v[64:79], v[218:221], v[112:115], v[64:79]
	ds_read_b128 v[214:217], v169 offset:24832
	ds_read_b128 v[218:221], v169 offset:37120
	s_waitcnt lgkmcnt(0)
	v_mfma_f32_32x32x16_bf16 v[80:95], v[214:217], v[108:111], v[80:95]
	v_mfma_f32_32x32x16_bf16 v[64:79], v[218:221], v[108:111], v[64:79]
	ds_read_b128 v[214:217], v190 offset:24832
	ds_read_b128 v[218:221], v190 offset:37120
	s_waitcnt lgkmcnt(0)
	v_mfma_f32_32x32x16_bf16 v[80:95], v[214:217], v[104:107], v[80:95]
	v_mfma_f32_32x32x16_bf16 v[64:79], v[218:221], v[104:107], v[64:79]
	ds_read_b128 v[214:217], v193 offset:24832
	ds_read_b128 v[218:221], v193 offset:37120
	s_waitcnt lgkmcnt(0)
	v_mfma_f32_32x32x16_bf16 v[80:95], v[214:217], v[100:103], v[80:95]
	v_mfma_f32_32x32x16_bf16 v[64:79], v[218:221], v[100:103], v[64:79]
	ds_read_b128 v[214:217], v192 offset:24832
	ds_read_b128 v[218:221], v192 offset:37120
	s_waitcnt lgkmcnt(0)
	v_mfma_f32_32x32x16_bf16 v[80:95], v[214:217], v[96:99], v[80:95]
	v_mov_b32_e32 v214, v159
	v_mov_b32_e32 v215, v152
	v_mov_b32_e32 v216, v153
	v_mov_b32_e32 v217, v150
	v_add_f32_e32 v247, v214, v247
	v_add_f32_e32 v251, v215, v251
	v_add_f32_e32 v252, v216, v252
	v_mfma_f32_32x32x16_bf16 v[64:79], v[218:221], v[96:99], v[64:79]
	v_mov_b32_e32 v218, v151
	v_mov_b32_e32 v219, v148
	v_mov_b32_e32 v220, v149
	v_mov_b32_e32 v221, v146
	v_add_f32_e32 v144, v217, v144
	v_add_f32_e32 v243, v218, v243
	v_add_f32_e32 v244, v219, v244
	v_add_f32_e32 v245, v220, v245
	v_add_f32_e32 v246, v221, v246
	v_add_f32_e32 v247, v222, v247
	v_add_f32_e32 v251, v223, v251
	v_add_f32_e32 v252, v224, v252
	v_add_f32_e32 v144, v144, v243
	v_add_f32_e32 v244, v244, v245
	v_add_f32_e32 v246, v246, v247
	v_add_f32_e32 v251, v251, v252
	v_add_f32_e32 v144, v144, v244
	v_add_f32_e32 v246, v246, v251
	v_add_f32_e32 v158, v144, v246
	v_mov_b32_e32 v159, v158
	v_cvt_pk_bf16_f32 v144, v145, v210
	v_cvt_pk_bf16_f32 v145, v208, v212
	v_cvt_pk_bf16_f32 v146, v211, v213
	v_cvt_pk_bf16_f32 v147, v207, v209
	v_cvt_pk_bf16_f32 v148, v200, v203
	v_cvt_pk_bf16_f32 v149, v202, v205
	v_cvt_pk_bf16_f32 v150, v199, v201
	v_cvt_pk_bf16_f32 v151, v204, v206
	v_cvt_pk_bf16_f32 v152, v172, v173
	v_cvt_pk_bf16_f32 v153, v170, v171
	v_cvt_pk_bf16_f32 v154, v196, v214
	s_nop 1
	v_permlane32_swap_b32_e32 v158, v159
	v_cvt_pk_bf16_f32 v155, v215, v216
	v_cvt_pk_bf16_f32 v170, v217, v218
	v_cvt_pk_bf16_f32 v171, v219, v220
	v_cvt_pk_bf16_f32 v172, v221, v222
	v_cvt_pk_bf16_f32 v173, v223, v224
	v_readlane_b32 s58, v249, 37
	v_readlane_b32 s59, v249, 38
	s_add_u32 s56, s58, s47
	s_addc_u32 s57, s59, s50
	s_add_u32 s4, s56, 0x17060000
	s_addc_u32 s5, s57, 0
	s_add_u32 s58, s58, s14
	s_addc_u32 s59, s59, s15
	s_add_u32 s60, s58, 0x1a040000
	s_mov_b32 m0, s41
	s_addc_u32 s61, s59, 0
	s_lshl_b32 s52, s54, 14
	s_add_i32 s62, s40, s52
	global_load_lds_dwordx4 v188, s[4:5]
	s_mov_b32 m0, s42
	s_nop 0
	global_load_lds_dwordx4 v189, s[4:5]
	s_add_i32 m0, s41, 0x4000
	s_nop 0
	global_load_lds_dwordx4 v191, s[4:5]
	s_mov_b32 m0, s62
	s_nop 0
	global_load_lds_dwordx4 v194, s[60:61]
	s_add_i32 m0, s62, 0x2000
	s_nop 0
	global_load_lds_dwordx4 v195, s[60:61]
	s_lshl_b32 s60, s43, 14
	v_add_u32_e32 v196, s60, v167
	ds_read_b64_tr_b16 v[200:201], v196 offset:0
	ds_read_b64_tr_b16 v[202:203], v196 offset:0x800
	ds_read_b64_tr_b16 v[204:205], v196 offset:0x1000
	ds_read_b64_tr_b16 v[206:207], v196 offset:0x1800
	ds_read_b64_tr_b16 v[208:209], v196 offset:0x2000
	ds_read_b64_tr_b16 v[210:211], v196 offset:0x2800
	ds_read_b64_tr_b16 v[212:213], v196 offset:0x3000
	ds_read_b64_tr_b16 v[214:215], v196 offset:0x3800
	s_waitcnt lgkmcnt(0)
; #define RESC(a) do { if (__any((a) < 1.f)) { if (hi == 0) al_l[r32] = (a); asm volatile("s_waitcnt lgkmcnt(0)" ::: "memory"); \
;     for (int d = 0; d < 4; ++d) for (int r = 0; r < 16; ++r) o[d][r] *= al_l[crow_(r, hi)]; } } while (0)
; #define TILE_BAR() do { asm volatile("s_waitcnt vmcnt(0) lgkmcnt(0)" ::: "memory"); __builtin_amdgcn_s_barrier(); } while (0)
; #define RESC(a) do { if (__any((a) < 1.f)) { for (int d = 0; d < 4; ++d) for (int r = 0; r < 16; ++r) o[d][r] *= (a); } } while (0)
; #define TILE_BAR() do { asm volatile("s_waitcnt vmcnt(0) lgkmcnt(0)" ::: "memory"); __builtin_amdgcn_s_barrier(); } while (0)
; #define RESC(a) do { if (__any((a) < 1.f)) { for (int d = 0; d < 4; ++d) for (int r = 0; r < 16; ++r) o[d][r] *= (a); } } while (0)
; template <int MLA>
; __device__ __forceinline__ void partialSM(f32x16& p0, f32x16& p1, float& m_reg, float& mn, float& alpha) {
;   constexpr float SCALE = AttC<MLA>::SCALE;
;   constexpr float C = SCALE * 1.4426950408889634f;
;   float pmax = p0[0];
; #pragma unroll
;   for (int r = 1; r < 16; ++r) pmax = fmaxf(pmax, p0[r]);
; #pragma unroll
;   for (int r = 0; r < 16; ++r) pmax = fmaxf(pmax, p1[r]);
;   { auto rr = __builtin_amdgcn_permlane32_swap(__float_as_uint(pmax), __float_as_uint(pmax), false, false);
;     pmax = fmaxf(__uint_as_float(rr[0]), __uint_as_float(rr[1])); }
;   if (__builtin_expect(__all(pmax - m_reg <= THR / SCALE), 1)) { mn = m_reg; alpha = 1.f; }
;   else { mn = fmaxf(m_reg, pmax); alpha = __builtin_amdgcn_exp2f((m_reg - mn) * C); m_reg = mn; }
;   float mnC = -mn * C;
; #pragma unroll
;   for (int r = 0; r < 16; ++r) p0[r] = fmaf(p0[r], C, mnC);
; #pragma unroll
;   for (int r = 0; r < 16; ++r) p1[r] = fmaf(p1[r], C, mnC);
; #pragma unroll
;   for (int r = 0; r < 16; ++r) p0[r] = __builtin_amdgcn_exp2f(p0[r]);
; }
; __device__ __forceinline__ void attn_mla_dma(const bf16_t* __restrict__ Qb, const bf16_t* __restrict__ Kh, const bf16_t* __restrict__ Vh, bf16_t* __restrict__ Ob,
;                                              int seq, char* lds, const int tid) {
;     ...
;     pv_d0_t(o, vb0 + vprev * SHM_VV, pa0, pa1, pa2, pa3); partialSM<MLA>(pB0, pB1, m_reg, mnB, alB);
;     TILE_BAR();
;     RESC(alB);
;     { const int t = vprev; vprev = vcur; vcur = vnxt; vnxt = t; }
	s_nop 0
	v_mfma_f32_32x32x16_bf16 v[0:15], v[200:203], v[144:147], v[0:15]
	ds_read_b64_tr_b16 v[200:201], v196 offset:0x200
	ds_read_b64_tr_b16 v[202:203], v196 offset:0xa00
	v_mfma_f32_32x32x16_bf16 v[0:15], v[204:207], v[148:151], v[0:15]
	ds_read_b64_tr_b16 v[204:205], v196 offset:0x1200
	ds_read_b64_tr_b16 v[206:207], v196 offset:0x1a00
	v_mfma_f32_32x32x16_bf16 v[0:15], v[208:211], v[152:155], v[0:15]
	ds_read_b64_tr_b16 v[208:209], v196 offset:0x2200
	ds_read_b64_tr_b16 v[210:211], v196 offset:0x2a00
	v_mfma_f32_32x32x16_bf16 v[0:15], v[212:215], v[170:173], v[0:15]
	ds_read_b64_tr_b16 v[212:213], v196 offset:0x3200
	ds_read_b64_tr_b16 v[214:215], v196 offset:0x3a00
	s_waitcnt lgkmcnt(0)
	v_mfma_f32_32x32x16_bf16 v[48:63], v[200:203], v[144:147], v[48:63]
	ds_read_b64_tr_b16 v[200:201], v196 offset:0x400
	ds_read_b64_tr_b16 v[202:203], v196 offset:0xc00
	v_mfma_f32_32x32x16_bf16 v[48:63], v[204:207], v[148:151], v[48:63]
	ds_read_b64_tr_b16 v[204:205], v196 offset:0x1400
	ds_read_b64_tr_b16 v[206:207], v196 offset:0x1c00
	v_mfma_f32_32x32x16_bf16 v[48:63], v[208:211], v[152:155], v[48:63]
	ds_read_b64_tr_b16 v[208:209], v196 offset:0x2400
	ds_read_b64_tr_b16 v[210:211], v196 offset:0x2c00
	v_mfma_f32_32x32x16_bf16 v[48:63], v[212:215], v[170:173], v[48:63]
	ds_read_b64_tr_b16 v[212:213], v196 offset:0x3400
	ds_read_b64_tr_b16 v[214:215], v196 offset:0x3c00
	s_waitcnt lgkmcnt(0)
	v_mfma_f32_32x32x16_bf16 v[32:47], v[200:203], v[144:147], v[32:47]
	ds_read_b64_tr_b16 v[200:201], v196 offset:0x600
	ds_read_b64_tr_b16 v[202:203], v196 offset:0xe00
	v_mfma_f32_32x32x16_bf16 v[32:47], v[204:207], v[148:151], v[32:47]
	ds_read_b64_tr_b16 v[204:205], v196 offset:0x1600
	ds_read_b64_tr_b16 v[206:207], v196 offset:0x1e00
	v_mfma_f32_32x32x16_bf16 v[32:47], v[208:211], v[152:155], v[32:47]
	ds_read_b64_tr_b16 v[208:209], v196 offset:0x2600
	ds_read_b64_tr_b16 v[210:211], v196 offset:0x2e00
	v_mfma_f32_32x32x16_bf16 v[32:47], v[212:215], v[170:173], v[32:47]
	ds_read_b64_tr_b16 v[212:213], v196 offset:0x3600
	ds_read_b64_tr_b16 v[214:215], v196 offset:0x3e00
	s_waitcnt lgkmcnt(0)
	v_mfma_f32_32x32x16_bf16 v[16:31], v[200:203], v[144:147], v[16:31]
	v_max_f32_e32 v144, v80, v81
	v_max3_f32 v144, v144, v82, v83
	v_max3_f32 v144, v144, v84, v85
	v_max3_f32 v144, v144, v86, v87
	v_max3_f32 v144, v144, v88, v89
	v_max3_f32 v144, v144, v90, v91
	v_max3_f32 v144, v144, v92, v93
	v_mfma_f32_32x32x16_bf16 v[16:31], v[204:207], v[148:151], v[16:31]
	v_max3_f32 v144, v144, v94, v95
	v_max3_f32 v144, v144, v64, v65
	v_max3_f32 v144, v144, v66, v67
	v_max3_f32 v144, v144, v68, v69
	v_max3_f32 v144, v144, v70, v71
	v_max3_f32 v144, v144, v72, v73
	v_max3_f32 v144, v144, v74, v75
	v_max3_f32 v144, v144, v76, v77
	v_mfma_f32_32x32x16_bf16 v[16:31], v[208:211], v[152:155], v[16:31]
	v_max3_f32 v144, v144, v78, v79
	v_mov_b32_e32 v145, v144
	s_nop 1
	v_permlane32_swap_b32_e32 v144, v145
	v_max_f32_e32 v144, v144, v145
	v_cmp_ge_f32_e32 vcc, s63, v144
	v_mfma_f32_32x32x16_bf16 v[16:31], v[212:215], v[170:173], v[16:31]
	s_cmp_eq_u64 vcc, exec
	s_cselect_b64 s[4:5], -1, 0
	s_waitcnt vmcnt(0) lgkmcnt(0)
	s_barrier
	s_cbranch_scc1 .Lal_c_m1
	v_max_f32_e32 v242, 0, v144
	v_exp_f32_e64 v152, -v242
	s_nop 0
	v_pk_mul_f32 v[14:15], v[14:15], v[152:153] op_sel_hi:[1,0]
	v_pk_mul_f32 v[12:13], v[12:13], v[152:153] op_sel_hi:[1,0]
	v_pk_mul_f32 v[10:11], v[10:11], v[152:153] op_sel_hi:[1,0]
	v_pk_mul_f32 v[8:9], v[8:9], v[152:153] op_sel_hi:[1,0]
	v_pk_mul_f32 v[6:7], v[6:7], v[152:153] op_sel_hi:[1,0]
	v_pk_mul_f32 v[4:5], v[4:5], v[152:153] op_sel_hi:[1,0]
	v_pk_mul_f32 v[2:3], v[2:3], v[152:153] op_sel_hi:[1,0]
	v_pk_mul_f32 v[0:1], v[0:1], v[152:153] op_sel_hi:[1,0]
	v_pk_mul_f32 v[62:63], v[62:63], v[152:153] op_sel_hi:[1,0]
	v_pk_mul_f32 v[60:61], v[60:61], v[152:153] op_sel_hi:[1,0]
	v_pk_mul_f32 v[58:59], v[58:59], v[152:153] op_sel_hi:[1,0]
	v_pk_mul_f32 v[56:57], v[56:57], v[152:153] op_sel_hi:[1,0]
	v_pk_mul_f32 v[54:55], v[54:55], v[152:153] op_sel_hi:[1,0]
	v_pk_mul_f32 v[52:53], v[52:53], v[152:153] op_sel_hi:[1,0]
	v_pk_mul_f32 v[50:51], v[50:51], v[152:153] op_sel_hi:[1,0]
	v_pk_mul_f32 v[48:49], v[48:49], v[152:153] op_sel_hi:[1,0]
	v_pk_mul_f32 v[46:47], v[46:47], v[152:153] op_sel_hi:[1,0]
	v_pk_mul_f32 v[44:45], v[44:45], v[152:153] op_sel_hi:[1,0]
	v_pk_mul_f32 v[42:43], v[42:43], v[152:153] op_sel_hi:[1,0]
	v_pk_mul_f32 v[40:41], v[40:41], v[152:153] op_sel_hi:[1,0]
	v_pk_mul_f32 v[38:39], v[38:39], v[152:153] op_sel_hi:[1,0]
	v_pk_mul_f32 v[36:37], v[36:37], v[152:153] op_sel_hi:[1,0]
	v_pk_mul_f32 v[34:35], v[34:35], v[152:153] op_sel_hi:[1,0]
	v_pk_mul_f32 v[32:33], v[32:33], v[152:153] op_sel_hi:[1,0]
	v_pk_mul_f32 v[30:31], v[30:31], v[152:153] op_sel_hi:[1,0]
	v_pk_mul_f32 v[28:29], v[28:29], v[152:153] op_sel_hi:[1,0]
	v_pk_mul_f32 v[26:27], v[26:27], v[152:153] op_sel_hi:[1,0]
	v_pk_mul_f32 v[24:25], v[24:25], v[152:153] op_sel_hi:[1,0]
	v_pk_mul_f32 v[22:23], v[22:23], v[152:153] op_sel_hi:[1,0]
	v_pk_mul_f32 v[20:21], v[20:21], v[152:153] op_sel_hi:[1,0]
	v_pk_mul_f32 v[18:19], v[18:19], v[152:153] op_sel_hi:[1,0]
	v_pk_mul_f32 v[16:17], v[16:17], v[152:153] op_sel_hi:[1,0]
	v_sub_f32_e32 v80, v80, v242
	v_sub_f32_e32 v81, v81, v242
	v_sub_f32_e32 v82, v82, v242
	v_sub_f32_e32 v83, v83, v242
	v_sub_f32_e32 v84, v84, v242
	v_sub_f32_e32 v85, v85, v242
	v_sub_f32_e32 v86, v86, v242
	v_sub_f32_e32 v87, v87, v242
	v_sub_f32_e32 v88, v88, v242
	v_sub_f32_e32 v89, v89, v242
	v_sub_f32_e32 v90, v90, v242
	v_sub_f32_e32 v91, v91, v242
	v_sub_f32_e32 v92, v92, v242
	v_sub_f32_e32 v93, v93, v242
	v_sub_f32_e32 v94, v94, v242
	v_sub_f32_e32 v95, v95, v242
	v_sub_f32_e32 v64, v64, v242
	v_sub_f32_e32 v65, v65, v242
	v_sub_f32_e32 v66, v66, v242
	v_sub_f32_e32 v67, v67, v242
	v_sub_f32_e32 v68, v68, v242
	v_sub_f32_e32 v69, v69, v242
	v_sub_f32_e32 v70, v70, v242
	v_sub_f32_e32 v71, v71, v242
	v_sub_f32_e32 v72, v72, v242
	v_sub_f32_e32 v73, v73, v242
	v_sub_f32_e32 v74, v74, v242
	v_sub_f32_e32 v75, v75, v242
	v_sub_f32_e32 v76, v76, v242
	v_sub_f32_e32 v77, v77, v242
	v_sub_f32_e32 v78, v78, v242
	v_sub_f32_e32 v79, v79, v242
	v_sub_f32_e32 v226, v226, v242
	v_sub_f32_e32 v227, v227, v242
	v_sub_f32_e32 v228, v228, v242
	v_sub_f32_e32 v229, v229, v242
	v_sub_f32_e32 v230, v230, v242
	v_sub_f32_e32 v231, v231, v242
	v_sub_f32_e32 v232, v232, v242
	v_sub_f32_e32 v233, v233, v242
	v_sub_f32_e32 v234, v234, v242
	v_sub_f32_e32 v235, v235, v242
	v_sub_f32_e32 v236, v236, v242
	v_sub_f32_e32 v237, v237, v242
	v_sub_f32_e32 v238, v238, v242
	v_sub_f32_e32 v239, v239, v242
	v_sub_f32_e32 v240, v240, v242
	v_sub_f32_e32 v241, v241, v242
	s_branch .LBB0_117

; #define SBAR() __builtin_amdgcn_sched_barrier(0)
; __device__ __forceinline__ void finishSM(f32x16& p0, f32x16& p1, float alpha, float& l_reg, bf16x8& pa0, bf16x8& pa1, bf16x8& pa2, bf16x8& pa3) {
; #pragma unroll
;   for (int r = 0; r < 16; ++r) p1[r] = __builtin_amdgcn_exp2f(p1[r]);
;   float ps = 0;
; #pragma unroll
;   for (int r = 0; r < 16; ++r) ps += p0[r];
; #pragma unroll
;   for (int r = 0; r < 16; ++r) ps += p1[r];
;   { auto rr = __builtin_amdgcn_permlane32_swap(__float_as_uint(ps), __float_as_uint(ps), false, false);
;     ps = __uint_as_float(rr[0]) + __uint_as_float(rr[1]); }
;   l_reg = l_reg * alpha + ps;
; __device__ __forceinline__ void attn_mla_dma(const bf16_t* __restrict__ Qb, const bf16_t* __restrict__ Kh, const bf16_t* __restrict__ Vh, bf16_t* __restrict__ Ob,
;                                              int seq, char* lds, const int tid) {
;     ...
;     SBAR(); qkt_mla<0>(pA0, pA1, ka, qr, qlds);
;     finishSM(pB0, pB1, alB, l_reg, pa0, pa1, pa2, pa3); SBAR();
;     DMA_TILE((j + 2) * KVBLK, 1, vnxt); SBAR();
;     pv_d0_t(o, vb0 + vprev * SHM_VV, pa0, pa1, pa2, pa3); partialSM<MLA>(pA0, pA1, m_reg, mnA, alA);
.LBB0_117:
	v_exp_f32_e32 v155, v64
	v_exp_f32_e32 v170, v65
	v_exp_f32_e32 v171, v66
	v_exp_f32_e32 v172, v67
	v_exp_f32_e32 v173, v68
	v_exp_f32_e32 v197, v69
	v_exp_f32_e32 v199, v70
	v_exp_f32_e32 v200, v71
	v_exp_f32_e32 v201, v72
	v_exp_f32_e32 v202, v73
	v_exp_f32_e32 v203, v74
	v_exp_f32_e32 v204, v75
	v_exp_f32_e32 v205, v76
	v_exp_f32_e32 v222, v77
	v_exp_f32_e32 v223, v78
	v_exp_f32_e32 v154, v79
	v_exp_f32_e32 v206, v80
	v_exp_f32_e32 v207, v81
	v_exp_f32_e32 v208, v82
	v_exp_f32_e32 v209, v83
	v_exp_f32_e32 v210, v84
	v_exp_f32_e32 v211, v85
	v_exp_f32_e32 v212, v86
	v_exp_f32_e32 v213, v87
	v_exp_f32_e32 v214, v88
	v_exp_f32_e32 v215, v89
	v_exp_f32_e32 v216, v90
	v_exp_f32_e32 v217, v91
	v_exp_f32_e32 v218, v92
	v_exp_f32_e32 v219, v93
	v_exp_f32_e32 v220, v94
	v_exp_f32_e32 v221, v95
	ds_read_b128 v[64:67], v169
	ds_read_b128 v[68:71], v169 offset:12288
	ds_read_b128 v[144:147], v190
	ds_read_b128 v[148:151], v190 offset:12288
	v_mov_b32_e32 v224, v155
	s_waitcnt lgkmcnt(0)
	v_mfma_f32_32x32x16_bf16 v[80:95], v[64:67], v[140:143], v[226:241]
	v_mfma_f32_32x32x16_bf16 v[64:79], v[68:71], v[140:143], v[226:241]
	v_mov_b32_e32 v225, v154
	v_mfma_f32_32x32x16_bf16 v[80:95], v[144:147], v[136:139], v[80:95]
	v_mfma_f32_32x32x16_bf16 v[64:79], v[148:151], v[136:139], v[64:79]
	ds_read_b128 v[144:147], v193
	ds_read_b128 v[148:151], v193 offset:12288
	s_waitcnt lgkmcnt(0)
	v_mfma_f32_32x32x16_bf16 v[80:95], v[144:147], v[132:135], v[80:95]
	v_mfma_f32_32x32x16_bf16 v[64:79], v[148:151], v[132:135], v[64:79]
	ds_read_b128 v[144:147], v192
	ds_read_b128 v[148:151], v192 offset:12288
	s_waitcnt lgkmcnt(0)
	v_mfma_f32_32x32x16_bf16 v[80:95], v[144:147], v[128:131], v[80:95]
	v_mfma_f32_32x32x16_bf16 v[64:79], v[148:151], v[128:131], v[64:79]
	ds_read_b128 v[144:147], v169 offset:128
	ds_read_b128 v[148:151], v169 offset:12416
	s_waitcnt lgkmcnt(0)
	v_mfma_f32_32x32x16_bf16 v[80:95], v[144:147], v[124:127], v[80:95]
	v_mfma_f32_32x32x16_bf16 v[64:79], v[148:151], v[124:127], v[64:79]
	ds_read_b128 v[144:147], v190 offset:128
	ds_read_b128 v[148:151], v190 offset:12416
	s_waitcnt lgkmcnt(0)
	v_mfma_f32_32x32x16_bf16 v[80:95], v[144:147], v[120:123], v[80:95]
	v_mfma_f32_32x32x16_bf16 v[64:79], v[148:151], v[120:123], v[64:79]
	ds_read_b128 v[144:147], v193 offset:128
	ds_read_b128 v[148:151], v193 offset:12416
	s_waitcnt lgkmcnt(0)
	v_mfma_f32_32x32x16_bf16 v[80:95], v[144:147], v[116:119], v[80:95]
	v_mfma_f32_32x32x16_bf16 v[64:79], v[148:151], v[116:119], v[64:79]
	ds_read_b128 v[144:147], v192 offset:128
	ds_read_b128 v[148:151], v192 offset:12416
	s_waitcnt lgkmcnt(0)
	v_mfma_f32_32x32x16_bf16 v[80:95], v[144:147], v[112:115], v[80:95]
	v_mfma_f32_32x32x16_bf16 v[64:79], v[148:151], v[112:115], v[64:79]
	ds_read_b128 v[144:147], v169 offset:256
	ds_read_b128 v[148:151], v169 offset:12544
	s_waitcnt lgkmcnt(0)
	v_mfma_f32_32x32x16_bf16 v[80:95], v[144:147], v[108:111], v[80:95]
	v_mfma_f32_32x32x16_bf16 v[64:79], v[148:151], v[108:111], v[64:79]
	ds_read_b128 v[144:147], v190 offset:256
	ds_read_b128 v[148:151], v190 offset:12544
	s_waitcnt lgkmcnt(0)
	v_mfma_f32_32x32x16_bf16 v[80:95], v[144:147], v[104:107], v[80:95]
	v_mfma_f32_32x32x16_bf16 v[64:79], v[148:151], v[104:107], v[64:79]
	ds_read_b128 v[144:147], v193 offset:256
	ds_read_b128 v[148:151], v193 offset:12544
	s_waitcnt lgkmcnt(0)
	v_mfma_f32_32x32x16_bf16 v[80:95], v[144:147], v[100:103], v[80:95]
	v_mfma_f32_32x32x16_bf16 v[64:79], v[148:151], v[100:103], v[64:79]
	ds_read_b128 v[144:147], v192 offset:256
	ds_read_b128 v[148:151], v192 offset:12544
	s_waitcnt lgkmcnt(0)
	v_mfma_f32_32x32x16_bf16 v[80:95], v[144:147], v[96:99], v[80:95]
	v_add_f32_e32 v144, v214, v206
	v_add_f32_e32 v243, v215, v207
	v_add_f32_e32 v244, v216, v208
	v_add_f32_e32 v245, v217, v209
	v_add_f32_e32 v246, v218, v210
	v_add_f32_e32 v247, v219, v211
	v_add_f32_e32 v251, v220, v212
	v_add_f32_e32 v252, v221, v213
	v_add_f32_e32 v144, v224, v144
	v_add_f32_e32 v243, v170, v243
	v_add_f32_e32 v244, v171, v244
	v_add_f32_e32 v245, v172, v245
	v_add_f32_e32 v246, v173, v246
	v_add_f32_e32 v247, v197, v247
	v_add_f32_e32 v251, v199, v251
	v_add_f32_e32 v252, v200, v252
	v_add_f32_e32 v144, v201, v144
	v_add_f32_e32 v243, v202, v243
	v_mfma_f32_32x32x16_bf16 v[64:79], v[148:151], v[96:99], v[64:79]
	v_add_f32_e32 v244, v203, v244
	v_add_f32_e32 v245, v204, v245
	v_add_f32_e32 v246, v205, v246
	v_add_f32_e32 v247, v222, v247
	v_add_f32_e32 v251, v223, v251
	v_add_f32_e32 v252, v225, v252
	v_add_f32_e32 v144, v144, v243
	v_add_f32_e32 v244, v244, v245
	v_add_f32_e32 v246, v246, v247
	v_add_f32_e32 v251, v251, v252
	v_add_f32_e32 v144, v144, v244
	v_add_f32_e32 v246, v246, v251
	v_add_f32_e32 v154, v144, v246
	v_mov_b32_e32 v155, v154
	v_cvt_pk_bf16_f32 v144, v206, v207
	v_cvt_pk_bf16_f32 v145, v208, v209
	v_cvt_pk_bf16_f32 v146, v210, v211
	v_cvt_pk_bf16_f32 v147, v212, v213
	s_nop 1
	v_permlane32_swap_b32_e32 v154, v155
	v_cvt_pk_bf16_f32 v148, v214, v215
	v_cvt_pk_bf16_f32 v149, v216, v217
	v_cvt_pk_bf16_f32 v150, v218, v219
	v_cvt_pk_bf16_f32 v151, v220, v221
	v_cvt_pk_bf16_f32 v170, v224, v170
	v_cvt_pk_bf16_f32 v171, v171, v172
	v_cvt_pk_bf16_f32 v172, v173, v197
	v_cvt_pk_bf16_f32 v173, v199, v200
	v_cvt_pk_bf16_f32 v200, v201, v202
	v_cvt_pk_bf16_f32 v201, v203, v204
	v_cvt_pk_bf16_f32 v202, v205, v222
	v_cvt_pk_bf16_f32 v203, v223, v225
	s_nop 0
	s_add_u32 s4, s56, 0x17090000
	s_addc_u32 s5, s57, 0
	s_add_u32 s56, s58, 0x1a060000
	s_mov_b32 m0, s16
	s_addc_u32 s57, s59, 0
	s_add_i32 s58, s40, s60
	global_load_lds_dwordx4 v188, s[4:5]
	s_mov_b32 m0, s17
	s_nop 0
	global_load_lds_dwordx4 v189, s[4:5]
	s_mov_b32 m0, s44
	s_nop 0
	global_load_lds_dwordx4 v191, s[4:5]
	s_mov_b32 m0, s58
	s_nop 0
	global_load_lds_dwordx4 v194, s[56:57]
	s_add_i32 m0, s58, 0x2000
	s_nop 0
	global_load_lds_dwordx4 v195, s[56:57]
	v_lshl_add_u32 v197, s55, 14, v167
	ds_read_b64_tr_b16 v[204:205], v197 offset:0
	ds_read_b64_tr_b16 v[206:207], v197 offset:0x800
	ds_read_b64_tr_b16 v[208:209], v197 offset:0x1000
	ds_read_b64_tr_b16 v[210:211], v197 offset:0x1800
	ds_read_b64_tr_b16 v[212:213], v197 offset:0x2000
	ds_read_b64_tr_b16 v[214:215], v197 offset:0x2800
	ds_read_b64_tr_b16 v[216:217], v197 offset:0x3000
	ds_read_b64_tr_b16 v[218:219], v197 offset:0x3800
	s_waitcnt lgkmcnt(0)
; #define RESC(a) do { if (__any((a) < 1.f)) { if (hi == 0) al_l[r32] = (a); asm volatile("s_waitcnt lgkmcnt(0)" ::: "memory"); \
;     for (int d = 0; d < 4; ++d) for (int r = 0; r < 16; ++r) o[d][r] *= al_l[crow_(r, hi)]; } } while (0)
; #define TILE_BAR() do { asm volatile("s_waitcnt vmcnt(0) lgkmcnt(0)" ::: "memory"); __builtin_amdgcn_s_barrier(); } while (0)
; #define RESC(a) do { if (__any((a) < 1.f)) { for (int d = 0; d < 4; ++d) for (int r = 0; r < 16; ++r) o[d][r] *= (a); } } while (0)
; #define TILE_BAR() do { asm volatile("s_waitcnt vmcnt(0) lgkmcnt(0)" ::: "memory"); __builtin_amdgcn_s_barrier(); } while (0)
; #define RESC(a) do { if (__any((a) < 1.f)) { for (int d = 0; d < 4; ++d) for (int r = 0; r < 16; ++r) o[d][r] *= (a); } } while (0)
; template <int MLA>
; __device__ __forceinline__ void partialSM(f32x16& p0, f32x16& p1, float& m_reg, float& mn, float& alpha) {
;   constexpr float SCALE = AttC<MLA>::SCALE;
;   constexpr float C = SCALE * 1.4426950408889634f;
;   float pmax = p0[0];
; #pragma unroll
;   for (int r = 1; r < 16; ++r) pmax = fmaxf(pmax, p0[r]);
; #pragma unroll
;   for (int r = 0; r < 16; ++r) pmax = fmaxf(pmax, p1[r]);
;   { auto rr = __builtin_amdgcn_permlane32_swap(__float_as_uint(pmax), __float_as_uint(pmax), false, false);
;     pmax = fmaxf(__uint_as_float(rr[0]), __uint_as_float(rr[1])); }
;   if (__builtin_expect(__all(pmax - m_reg <= THR / SCALE), 1)) { mn = m_reg; alpha = 1.f; }
;   else { mn = fmaxf(m_reg, pmax); alpha = __builtin_amdgcn_exp2f((m_reg - mn) * C); m_reg = mn; }
;   float mnC = -mn * C;
; #pragma unroll
;   for (int r = 0; r < 16; ++r) p0[r] = fmaf(p0[r], C, mnC);
; #pragma unroll
;   for (int r = 0; r < 16; ++r) p1[r] = fmaf(p1[r], C, mnC);
; #pragma unroll
;   for (int r = 0; r < 16; ++r) p0[r] = __builtin_amdgcn_exp2f(p0[r]);
; }
; __device__ __forceinline__ void attn_mla_dma(const bf16_t* __restrict__ Qb, const bf16_t* __restrict__ Kh, const bf16_t* __restrict__ Vh, bf16_t* __restrict__ Ob,
;                                              int seq, char* lds, const int tid) {
;     ...
;     pv_d0_t(o, vb0 + vprev * SHM_VV, pa0, pa1, pa2, pa3); partialSM<MLA>(pA0, pA1, m_reg, mnA, alA);
;     TILE_BAR();
;     RESC(alA);
;     { const int t = vprev; vprev = vcur; vcur = vnxt; vnxt = t; }
	s_nop 0
	v_mfma_f32_32x32x16_bf16 v[0:15], v[204:207], v[144:147], v[0:15]
	ds_read_b64_tr_b16 v[204:205], v197 offset:0x200
	ds_read_b64_tr_b16 v[206:207], v197 offset:0xa00
	v_mfma_f32_32x32x16_bf16 v[0:15], v[208:211], v[148:151], v[0:15]
	ds_read_b64_tr_b16 v[208:209], v197 offset:0x1200
	ds_read_b64_tr_b16 v[210:211], v197 offset:0x1a00
	v_mfma_f32_32x32x16_bf16 v[0:15], v[212:215], v[170:173], v[0:15]
	ds_read_b64_tr_b16 v[212:213], v197 offset:0x2200
	ds_read_b64_tr_b16 v[214:215], v197 offset:0x2a00
	v_mfma_f32_32x32x16_bf16 v[0:15], v[216:219], v[200:203], v[0:15]
	ds_read_b64_tr_b16 v[216:217], v197 offset:0x3200
	ds_read_b64_tr_b16 v[218:219], v197 offset:0x3a00
	s_waitcnt lgkmcnt(0)
	v_mfma_f32_32x32x16_bf16 v[48:63], v[204:207], v[144:147], v[48:63]
	ds_read_b64_tr_b16 v[204:205], v197 offset:0x400
	ds_read_b64_tr_b16 v[206:207], v197 offset:0xc00
	v_mfma_f32_32x32x16_bf16 v[48:63], v[208:211], v[148:151], v[48:63]
	ds_read_b64_tr_b16 v[208:209], v197 offset:0x1400
	ds_read_b64_tr_b16 v[210:211], v197 offset:0x1c00
	v_mfma_f32_32x32x16_bf16 v[48:63], v[212:215], v[170:173], v[48:63]
	ds_read_b64_tr_b16 v[212:213], v197 offset:0x2400
	ds_read_b64_tr_b16 v[214:215], v197 offset:0x2c00
	v_mfma_f32_32x32x16_bf16 v[48:63], v[216:219], v[200:203], v[48:63]
	ds_read_b64_tr_b16 v[216:217], v197 offset:0x3400
	ds_read_b64_tr_b16 v[218:219], v197 offset:0x3c00
	s_waitcnt lgkmcnt(0)
	v_mfma_f32_32x32x16_bf16 v[32:47], v[204:207], v[144:147], v[32:47]
	ds_read_b64_tr_b16 v[204:205], v197 offset:0x600
	ds_read_b64_tr_b16 v[206:207], v197 offset:0xe00
	v_mfma_f32_32x32x16_bf16 v[32:47], v[208:211], v[148:151], v[32:47]
	ds_read_b64_tr_b16 v[208:209], v197 offset:0x1600
	ds_read_b64_tr_b16 v[210:211], v197 offset:0x1e00
	v_mfma_f32_32x32x16_bf16 v[32:47], v[212:215], v[170:173], v[32:47]
	ds_read_b64_tr_b16 v[212:213], v197 offset:0x2600
	ds_read_b64_tr_b16 v[214:215], v197 offset:0x2e00
	v_mfma_f32_32x32x16_bf16 v[32:47], v[216:219], v[200:203], v[32:47]
	ds_read_b64_tr_b16 v[216:217], v197 offset:0x3600
	ds_read_b64_tr_b16 v[218:219], v197 offset:0x3e00
	s_waitcnt lgkmcnt(0)
	v_mfma_f32_32x32x16_bf16 v[16:31], v[204:207], v[144:147], v[16:31]
	v_max_f32_e32 v144, v80, v81
	v_max3_f32 v144, v144, v82, v83
	v_max3_f32 v144, v144, v84, v85
	v_max3_f32 v144, v144, v86, v87
	v_max3_f32 v144, v144, v88, v89
	v_max3_f32 v144, v144, v90, v91
	v_max3_f32 v144, v144, v92, v93
	v_mfma_f32_32x32x16_bf16 v[16:31], v[208:211], v[148:151], v[16:31]
	v_max3_f32 v144, v144, v94, v95
	v_max3_f32 v144, v144, v64, v65
	v_max3_f32 v144, v144, v66, v67
	v_max3_f32 v144, v144, v68, v69
	v_max3_f32 v144, v144, v70, v71
	v_max3_f32 v144, v144, v72, v73
	v_max3_f32 v144, v144, v74, v75
	v_max3_f32 v144, v144, v76, v77
	v_mfma_f32_32x32x16_bf16 v[16:31], v[212:215], v[170:173], v[16:31]
	v_max3_f32 v144, v144, v78, v79
	v_mov_b32_e32 v145, v144
	s_nop 1
	v_permlane32_swap_b32_e32 v144, v145
	v_max_f32_e32 v144, v144, v145
	v_cmp_ge_f32_e32 vcc, s63, v144
	v_mfma_f32_32x32x16_bf16 v[16:31], v[216:219], v[200:203], v[16:31]
	s_cmp_eq_u64 vcc, exec
	s_cselect_b64 s[4:5], -1, 0
	s_waitcnt vmcnt(0) lgkmcnt(0)
	s_barrier
	s_cbranch_scc1 .Lal_c_m2
	v_max_f32_e32 v242, 0, v144
	v_exp_f32_e64 v144, -v242
	s_nop 0
	v_pk_mul_f32 v[14:15], v[14:15], v[144:145] op_sel_hi:[1,0]
	v_pk_mul_f32 v[12:13], v[12:13], v[144:145] op_sel_hi:[1,0]
	v_pk_mul_f32 v[10:11], v[10:11], v[144:145] op_sel_hi:[1,0]
	v_pk_mul_f32 v[8:9], v[8:9], v[144:145] op_sel_hi:[1,0]
	v_pk_mul_f32 v[6:7], v[6:7], v[144:145] op_sel_hi:[1,0]
	v_pk_mul_f32 v[4:5], v[4:5], v[144:145] op_sel_hi:[1,0]
	v_pk_mul_f32 v[2:3], v[2:3], v[144:145] op_sel_hi:[1,0]
	v_pk_mul_f32 v[0:1], v[0:1], v[144:145] op_sel_hi:[1,0]
	v_pk_mul_f32 v[62:63], v[62:63], v[144:145] op_sel_hi:[1,0]
	v_pk_mul_f32 v[60:61], v[60:61], v[144:145] op_sel_hi:[1,0]
	v_pk_mul_f32 v[58:59], v[58:59], v[144:145] op_sel_hi:[1,0]
	v_pk_mul_f32 v[56:57], v[56:57], v[144:145] op_sel_hi:[1,0]
	v_pk_mul_f32 v[54:55], v[54:55], v[144:145] op_sel_hi:[1,0]
	v_pk_mul_f32 v[52:53], v[52:53], v[144:145] op_sel_hi:[1,0]
	v_pk_mul_f32 v[50:51], v[50:51], v[144:145] op_sel_hi:[1,0]
	v_pk_mul_f32 v[48:49], v[48:49], v[144:145] op_sel_hi:[1,0]
	v_pk_mul_f32 v[46:47], v[46:47], v[144:145] op_sel_hi:[1,0]
	v_pk_mul_f32 v[44:45], v[44:45], v[144:145] op_sel_hi:[1,0]
	v_pk_mul_f32 v[42:43], v[42:43], v[144:145] op_sel_hi:[1,0]
	v_pk_mul_f32 v[40:41], v[40:41], v[144:145] op_sel_hi:[1,0]
	v_pk_mul_f32 v[38:39], v[38:39], v[144:145] op_sel_hi:[1,0]
	v_pk_mul_f32 v[36:37], v[36:37], v[144:145] op_sel_hi:[1,0]
	v_pk_mul_f32 v[34:35], v[34:35], v[144:145] op_sel_hi:[1,0]
	v_pk_mul_f32 v[32:33], v[32:33], v[144:145] op_sel_hi:[1,0]
	v_pk_mul_f32 v[30:31], v[30:31], v[144:145] op_sel_hi:[1,0]
	v_pk_mul_f32 v[28:29], v[28:29], v[144:145] op_sel_hi:[1,0]
	v_pk_mul_f32 v[26:27], v[26:27], v[144:145] op_sel_hi:[1,0]
	v_pk_mul_f32 v[24:25], v[24:25], v[144:145] op_sel_hi:[1,0]
	v_pk_mul_f32 v[22:23], v[22:23], v[144:145] op_sel_hi:[1,0]
	v_pk_mul_f32 v[20:21], v[20:21], v[144:145] op_sel_hi:[1,0]
	v_pk_mul_f32 v[18:19], v[18:19], v[144:145] op_sel_hi:[1,0]
	v_pk_mul_f32 v[16:17], v[16:17], v[144:145] op_sel_hi:[1,0]
	v_sub_f32_e32 v80, v80, v242
	v_sub_f32_e32 v81, v81, v242
	v_sub_f32_e32 v82, v82, v242
	v_sub_f32_e32 v83, v83, v242
	v_sub_f32_e32 v84, v84, v242
	v_sub_f32_e32 v85, v85, v242
	v_sub_f32_e32 v86, v86, v242
	v_sub_f32_e32 v87, v87, v242
	v_sub_f32_e32 v88, v88, v242
	v_sub_f32_e32 v89, v89, v242
	v_sub_f32_e32 v90, v90, v242
	v_sub_f32_e32 v91, v91, v242
	v_sub_f32_e32 v92, v92, v242
	v_sub_f32_e32 v93, v93, v242
	v_sub_f32_e32 v94, v94, v242
	v_sub_f32_e32 v95, v95, v242
	v_sub_f32_e32 v64, v64, v242
	v_sub_f32_e32 v65, v65, v242
	v_sub_f32_e32 v66, v66, v242
	v_sub_f32_e32 v67, v67, v242
	v_sub_f32_e32 v68, v68, v242
	v_sub_f32_e32 v69, v69, v242
	v_sub_f32_e32 v70, v70, v242
	v_sub_f32_e32 v71, v71, v242
	v_sub_f32_e32 v72, v72, v242
	v_sub_f32_e32 v73, v73, v242
	v_sub_f32_e32 v74, v74, v242
	v_sub_f32_e32 v75, v75, v242
	v_sub_f32_e32 v76, v76, v242
	v_sub_f32_e32 v77, v77, v242
	v_sub_f32_e32 v78, v78, v242
	v_sub_f32_e32 v79, v79, v242
	v_sub_f32_e32 v226, v226, v242
	v_sub_f32_e32 v227, v227, v242
	v_sub_f32_e32 v228, v228, v242
	v_sub_f32_e32 v229, v229, v242
	v_sub_f32_e32 v230, v230, v242
	v_sub_f32_e32 v231, v231, v242
	v_sub_f32_e32 v232, v232, v242
	v_sub_f32_e32 v233, v233, v242
	v_sub_f32_e32 v234, v234, v242
	v_sub_f32_e32 v235, v235, v242
	v_sub_f32_e32 v236, v236, v242
	v_sub_f32_e32 v237, v237, v242
	v_sub_f32_e32 v238, v238, v242
	v_sub_f32_e32 v239, v239, v242
	v_sub_f32_e32 v240, v240, v242
	v_sub_f32_e32 v241, v241, v242
	s_branch .LBB0_119

; #define SBAR() __builtin_amdgcn_sched_barrier(0)
; __device__ __forceinline__ void finishSM(f32x16& p0, f32x16& p1, float alpha, float& l_reg, bf16x8& pa0, bf16x8& pa1, bf16x8& pa2, bf16x8& pa3) {
; #pragma unroll
;   for (int r = 0; r < 16; ++r) p1[r] = __builtin_amdgcn_exp2f(p1[r]);
;   float ps = 0;
; #pragma unroll
;   for (int r = 0; r < 16; ++r) ps += p0[r];
; #pragma unroll
;   for (int r = 0; r < 16; ++r) ps += p1[r];
;   { auto rr = __builtin_amdgcn_permlane32_swap(__float_as_uint(ps), __float_as_uint(ps), false, false);
;     ps = __uint_as_float(rr[0]) + __uint_as_float(rr[1]); }
;   l_reg = l_reg * alpha + ps;
; __device__ __forceinline__ void attn_diff_dma(const bf16_t* __restrict__ Qb, const bf16_t* __restrict__ Kh, const bf16_t* __restrict__ Vh, bf16_t* __restrict__ Ob,
;                                               int seq, char* lds, float lam, const float* __restrict__ gsub, const int tid) {
;     ...
;     SBAR(); qkt_diff<(int)SHM_K128>(pB0, pB1, ka, qr);
;     finishSM(pA0, pA1, alA, l_reg, pa0, pa1, pa2, pa3); SBAR();
;     DMA_TILE((j + 1) * KVBLK, 0, vnxt); SBAR();
;     pv_d0_t(o, vb0 + vprev * SHM_VV, pa0, pa1, pa2, pa3); partialSM<0>(pB0, pB1, m_reg, mnB, alB);
.LBB0_129:
	s_mov_b32 s54, s47
	s_mov_b32 s47, s52
	ds_read_b128 v[64:67], v138 offset:16384
	ds_read_b128 v[68:71], v138 offset:24576
	ds_read_b128 v[170:173], v141 offset:16384
	ds_read_b128 v[188:191], v141 offset:24576
	s_waitcnt lgkmcnt(0)
	v_mfma_f32_32x32x16_bf16 v[80:95], v[64:67], v[108:111], v[226:241]
	v_add_f32_e32 v112, v144, v113
	v_mfma_f32_32x32x16_bf16 v[64:79], v[68:71], v[108:111], v[226:241]
	v_add_f32_e32 v243, v148, v155
	v_add_f32_e32 v244, v145, v152
	v_add_f32_e32 v245, v149, v156
	v_add_f32_e32 v246, v146, v153
	v_add_f32_e32 v247, v150, v158
	v_mfma_f32_32x32x16_bf16 v[80:95], v[170:173], v[104:107], v[80:95]
	v_add_f32_e32 v251, v147, v154
	v_add_f32_e32 v252, v151, v159
	v_mov_b32_e32 v132, v124
	v_add_f32_e32 v112, v128, v112
	v_mov_b32_e32 v162, v125
	v_mfma_f32_32x32x16_bf16 v[64:79], v[188:191], v[104:107], v[64:79]
	ds_read_b128 v[170:173], v140 offset:16384
	ds_read_b128 v[188:191], v140 offset:24576
	v_add_f32_e32 v243, v129, v243
	v_mov_b32_e32 v167, v120
	v_add_f32_e32 v244, v126, v244
	v_mov_b32_e32 v169, v121
	v_add_f32_e32 v245, v127, v245
	v_add_f32_e32 v246, v132, v246
	s_waitcnt lgkmcnt(0)
	v_mfma_f32_32x32x16_bf16 v[80:95], v[170:173], v[100:103], v[80:95]
	v_add_f32_e32 v247, v162, v247
	v_add_f32_e32 v251, v167, v251
	v_add_f32_e32 v252, v169, v252
	v_mfma_f32_32x32x16_bf16 v[64:79], v[188:191], v[100:103], v[64:79]
	ds_read_b128 v[170:173], v139 offset:16384
	ds_read_b128 v[188:191], v139 offset:24576
	s_waitcnt lgkmcnt(0)
	v_mfma_f32_32x32x16_bf16 v[80:95], v[170:173], v[96:99], v[80:95]
	v_mov_b32_e32 v170, v118
	v_mov_b32_e32 v171, v117
	v_mov_b32_e32 v172, v114
	v_mov_b32_e32 v173, v115
	v_add_f32_e32 v112, v170, v112
	v_add_f32_e32 v243, v119, v243
	v_add_f32_e32 v244, v116, v244
	v_mfma_f32_32x32x16_bf16 v[64:79], v[188:191], v[96:99], v[64:79]
	v_mov_b32_e32 v188, v122
	v_mov_b32_e32 v189, v123
	v_add_f32_e32 v245, v171, v245
	v_add_f32_e32 v246, v172, v246
	v_add_f32_e32 v247, v173, v247
	v_add_f32_e32 v251, v188, v251
	v_add_f32_e32 v252, v189, v252
	v_add_f32_e32 v112, v112, v243
	v_add_f32_e32 v244, v244, v245
	v_add_f32_e32 v246, v246, v247
	v_add_f32_e32 v251, v251, v252
	v_add_f32_e32 v112, v112, v244
	v_add_f32_e32 v246, v246, v251
	v_add_f32_e32 v117, v112, v246
	v_mov_b32_e32 v118, v117
	v_cvt_pk_bf16_f32 v112, v113, v155
	v_cvt_pk_bf16_f32 v113, v152, v156
	v_cvt_pk_bf16_f32 v114, v153, v158
	s_nop 1
	v_permlane32_swap_b32_e32 v117, v118
	v_cvt_pk_bf16_f32 v115, v154, v159
	v_cvt_pk_bf16_f32 v120, v144, v148
	v_cvt_pk_bf16_f32 v121, v145, v149
	v_cvt_pk_bf16_f32 v122, v146, v150
	v_cvt_pk_bf16_f32 v123, v147, v151
	v_cvt_pk_bf16_f32 v124, v128, v129
	v_cvt_pk_bf16_f32 v125, v126, v127
	v_cvt_pk_bf16_f32 v126, v132, v162
	v_cvt_pk_bf16_f32 v127, v167, v169
	v_cvt_pk_bf16_f32 v144, v170, v119
	v_cvt_pk_bf16_f32 v145, v116, v171
	v_cvt_pk_bf16_f32 v146, v172, v173
	v_cvt_pk_bf16_f32 v147, v188, v189
	s_add_u32 s4, s14, 0x2000000
	s_mov_b32 m0, s43
	s_addc_u32 s5, s15, 0
	s_mov_b64 s[56:57], s[14:15]
	s_lshl_b32 s52, s53, 14
	s_add_i32 s55, s42, s52
	s_nop 0
	global_load_lds_dwordx4 v134, s[56:57]
	s_mov_b32 m0, s44
	s_nop 0
	global_load_lds_dwordx4 v135, s[56:57]
	s_mov_b32 m0, s55
	s_nop 0
	global_load_lds_dwordx4 v136, s[4:5]
	s_add_i32 m0, s55, 0x2000
	s_nop 0
	global_load_lds_dwordx4 v137, s[4:5]
	s_lshl_b32 s55, s47, 14
	v_add_u32_e32 v132, s55, v133
	ds_read_b64_tr_b16 v[148:149], v132 offset:0
	ds_read_b64_tr_b16 v[150:151], v132 offset:0x800
	ds_read_b64_tr_b16 v[152:153], v132 offset:0x1000
	ds_read_b64_tr_b16 v[154:155], v132 offset:0x1800
	ds_read_b64_tr_b16 v[170:171], v132 offset:0x2000
	ds_read_b64_tr_b16 v[172:173], v132 offset:0x2800
	ds_read_b64_tr_b16 v[188:189], v132 offset:0x3000
	ds_read_b64_tr_b16 v[190:191], v132 offset:0x3800
	s_waitcnt lgkmcnt(0)
	s_nop 0
	v_mfma_f32_32x32x16_bf16 v[32:47], v[148:151], v[112:115], v[32:47]
	ds_read_b64_tr_b16 v[148:149], v132 offset:0x200
	ds_read_b64_tr_b16 v[150:151], v132 offset:0xa00
	v_mfma_f32_32x32x16_bf16 v[32:47], v[152:155], v[120:123], v[32:47]
	ds_read_b64_tr_b16 v[152:153], v132 offset:0x1200
	ds_read_b64_tr_b16 v[154:155], v132 offset:0x1a00
	v_mfma_f32_32x32x16_bf16 v[32:47], v[170:173], v[124:127], v[32:47]
	ds_read_b64_tr_b16 v[170:171], v132 offset:0x2200
	ds_read_b64_tr_b16 v[172:173], v132 offset:0x2a00
	v_mfma_f32_32x32x16_bf16 v[32:47], v[188:191], v[144:147], v[32:47]
	ds_read_b64_tr_b16 v[188:189], v132 offset:0x3200
	ds_read_b64_tr_b16 v[190:191], v132 offset:0x3a00
	s_waitcnt lgkmcnt(0)
	v_mfma_f32_32x32x16_bf16 v[48:63], v[148:151], v[112:115], v[48:63]
	ds_read_b64_tr_b16 v[148:149], v132 offset:0x400
	ds_read_b64_tr_b16 v[150:151], v132 offset:0xc00
	v_mfma_f32_32x32x16_bf16 v[48:63], v[152:155], v[120:123], v[48:63]
	ds_read_b64_tr_b16 v[152:153], v132 offset:0x1400
	ds_read_b64_tr_b16 v[154:155], v132 offset:0x1c00
	v_mfma_f32_32x32x16_bf16 v[48:63], v[170:173], v[124:127], v[48:63]
	ds_read_b64_tr_b16 v[170:171], v132 offset:0x2400
	ds_read_b64_tr_b16 v[172:173], v132 offset:0x2c00
	v_mfma_f32_32x32x16_bf16 v[48:63], v[188:191], v[144:147], v[48:63]
	ds_read_b64_tr_b16 v[188:189], v132 offset:0x3400
	ds_read_b64_tr_b16 v[190:191], v132 offset:0x3c00
	s_waitcnt lgkmcnt(0)
	v_mfma_f32_32x32x16_bf16 v[16:31], v[148:151], v[112:115], v[16:31]
	ds_read_b64_tr_b16 v[148:149], v132 offset:0x600
	ds_read_b64_tr_b16 v[150:151], v132 offset:0xe00
	v_mfma_f32_32x32x16_bf16 v[16:31], v[152:155], v[120:123], v[16:31]
	ds_read_b64_tr_b16 v[152:153], v132 offset:0x1600
	ds_read_b64_tr_b16 v[154:155], v132 offset:0x1e00
	v_mfma_f32_32x32x16_bf16 v[16:31], v[170:173], v[124:127], v[16:31]
	ds_read_b64_tr_b16 v[170:171], v132 offset:0x2600
	ds_read_b64_tr_b16 v[172:173], v132 offset:0x2e00
	v_mfma_f32_32x32x16_bf16 v[16:31], v[188:191], v[144:147], v[16:31]
	ds_read_b64_tr_b16 v[188:189], v132 offset:0x3600
	ds_read_b64_tr_b16 v[190:191], v132 offset:0x3e00
	s_waitcnt lgkmcnt(0)
	v_mfma_f32_32x32x16_bf16 v[0:15], v[148:151], v[112:115], v[0:15]
	v_max_f32_e32 v112, v80, v81
	v_max3_f32 v112, v112, v82, v83
	v_max3_f32 v112, v112, v84, v85
	v_max3_f32 v112, v112, v86, v87
	v_max3_f32 v112, v112, v88, v89
	v_max3_f32 v112, v112, v90, v91
	v_max3_f32 v112, v112, v92, v93
	v_mfma_f32_32x32x16_bf16 v[0:15], v[152:155], v[120:123], v[0:15]
	v_max3_f32 v112, v112, v94, v95
	v_max3_f32 v112, v112, v64, v65
	v_max3_f32 v112, v112, v66, v67
	v_max3_f32 v112, v112, v68, v69
	v_max3_f32 v112, v112, v70, v71
	v_max3_f32 v112, v112, v72, v73
	v_max3_f32 v112, v112, v74, v75
	v_max3_f32 v112, v112, v76, v77
	v_mfma_f32_32x32x16_bf16 v[0:15], v[170:173], v[124:127], v[0:15]
	v_max3_f32 v112, v112, v78, v79
	v_mov_b32_e32 v113, v112
	s_nop 1
	v_permlane32_swap_b32_e32 v112, v113
	v_max_f32_e32 v112, v112, v113
	v_cmp_ge_f32_e32 vcc, s70, v112
	v_mfma_f32_32x32x16_bf16 v[0:15], v[188:191], v[144:147], v[0:15]
	s_cmp_eq_u64 vcc, exec
	s_cselect_b64 s[4:5], -1, 0
	s_waitcnt vmcnt(0) lgkmcnt(0)
	s_barrier
; template <int MLA>
; __device__ __forceinline__ void partialSM(f32x16& p0, f32x16& p1, float& m_reg, float& mn, float& alpha) {
;     ...
;   if (__builtin_expect(__all(pmax - m_reg <= THR / SCALE), 1)) { mn = m_reg; alpha = 1.f; }
;   else { mn = fmaxf(m_reg, pmax); alpha = __builtin_amdgcn_exp2f((m_reg - mn) * C); m_reg = mn; }
;   float mnC = -mn * C;
; #pragma unroll
;   for (int r = 0; r < 16; ++r) p0[r] = fmaf(p0[r], C, mnC);
; #pragma unroll
;   for (int r = 0; r < 16; ++r) p1[r] = fmaf(p1[r], C, mnC);
	s_cbranch_scc1 .Lal_c_d1
	v_max_f32_e32 v242, 0, v112
	v_exp_f32_e64 v116, -v242
	s_nop 0
	v_pk_mul_f32 v[46:47], v[46:47], v[116:117] op_sel_hi:[1,0]
	v_pk_mul_f32 v[44:45], v[44:45], v[116:117] op_sel_hi:[1,0]
	v_pk_mul_f32 v[42:43], v[42:43], v[116:117] op_sel_hi:[1,0]
	v_pk_mul_f32 v[40:41], v[40:41], v[116:117] op_sel_hi:[1,0]
	v_pk_mul_f32 v[38:39], v[38:39], v[116:117] op_sel_hi:[1,0]
	v_pk_mul_f32 v[36:37], v[36:37], v[116:117] op_sel_hi:[1,0]
	v_pk_mul_f32 v[34:35], v[34:35], v[116:117] op_sel_hi:[1,0]
	v_pk_mul_f32 v[32:33], v[32:33], v[116:117] op_sel_hi:[1,0]
	v_pk_mul_f32 v[62:63], v[62:63], v[116:117] op_sel_hi:[1,0]
	v_pk_mul_f32 v[60:61], v[60:61], v[116:117] op_sel_hi:[1,0]
	v_pk_mul_f32 v[58:59], v[58:59], v[116:117] op_sel_hi:[1,0]
	v_pk_mul_f32 v[56:57], v[56:57], v[116:117] op_sel_hi:[1,0]
	v_pk_mul_f32 v[54:55], v[54:55], v[116:117] op_sel_hi:[1,0]
	v_pk_mul_f32 v[52:53], v[52:53], v[116:117] op_sel_hi:[1,0]
	v_pk_mul_f32 v[50:51], v[50:51], v[116:117] op_sel_hi:[1,0]
	v_pk_mul_f32 v[48:49], v[48:49], v[116:117] op_sel_hi:[1,0]
	v_pk_mul_f32 v[30:31], v[30:31], v[116:117] op_sel_hi:[1,0]
	v_pk_mul_f32 v[28:29], v[28:29], v[116:117] op_sel_hi:[1,0]
	v_pk_mul_f32 v[26:27], v[26:27], v[116:117] op_sel_hi:[1,0]
	v_pk_mul_f32 v[24:25], v[24:25], v[116:117] op_sel_hi:[1,0]
	v_pk_mul_f32 v[22:23], v[22:23], v[116:117] op_sel_hi:[1,0]
	v_pk_mul_f32 v[20:21], v[20:21], v[116:117] op_sel_hi:[1,0]
	v_pk_mul_f32 v[18:19], v[18:19], v[116:117] op_sel_hi:[1,0]
	v_pk_mul_f32 v[16:17], v[16:17], v[116:117] op_sel_hi:[1,0]
	v_pk_mul_f32 v[14:15], v[14:15], v[116:117] op_sel_hi:[1,0]
	v_pk_mul_f32 v[12:13], v[12:13], v[116:117] op_sel_hi:[1,0]
	v_pk_mul_f32 v[10:11], v[10:11], v[116:117] op_sel_hi:[1,0]
	v_pk_mul_f32 v[8:9], v[8:9], v[116:117] op_sel_hi:[1,0]
	v_pk_mul_f32 v[6:7], v[6:7], v[116:117] op_sel_hi:[1,0]
	v_pk_mul_f32 v[4:5], v[4:5], v[116:117] op_sel_hi:[1,0]
	v_pk_mul_f32 v[2:3], v[2:3], v[116:117] op_sel_hi:[1,0]
	v_pk_mul_f32 v[0:1], v[0:1], v[116:117] op_sel_hi:[1,0]
	v_sub_f32_e32 v80, v80, v242
	v_sub_f32_e32 v81, v81, v242
	v_sub_f32_e32 v82, v82, v242
	v_sub_f32_e32 v83, v83, v242
	v_sub_f32_e32 v84, v84, v242
	v_sub_f32_e32 v85, v85, v242
	v_sub_f32_e32 v86, v86, v242
	v_sub_f32_e32 v87, v87, v242
	v_sub_f32_e32 v88, v88, v242
	v_sub_f32_e32 v89, v89, v242
	v_sub_f32_e32 v90, v90, v242
	v_sub_f32_e32 v91, v91, v242
	v_sub_f32_e32 v92, v92, v242
	v_sub_f32_e32 v93, v93, v242
	v_sub_f32_e32 v94, v94, v242
	v_sub_f32_e32 v95, v95, v242
	v_sub_f32_e32 v64, v64, v242
	v_sub_f32_e32 v65, v65, v242
	v_sub_f32_e32 v66, v66, v242
	v_sub_f32_e32 v67, v67, v242
	v_sub_f32_e32 v68, v68, v242
	v_sub_f32_e32 v69, v69, v242
	v_sub_f32_e32 v70, v70, v242
	v_sub_f32_e32 v71, v71, v242
	v_sub_f32_e32 v72, v72, v242
	v_sub_f32_e32 v73, v73, v242
	v_sub_f32_e32 v74, v74, v242
	v_sub_f32_e32 v75, v75, v242
	v_sub_f32_e32 v76, v76, v242
	v_sub_f32_e32 v77, v77, v242
	v_sub_f32_e32 v78, v78, v242
	v_sub_f32_e32 v79, v79, v242
	v_sub_f32_e32 v226, v226, v242
	v_sub_f32_e32 v227, v227, v242
	v_sub_f32_e32 v228, v228, v242
	v_sub_f32_e32 v229, v229, v242
	v_sub_f32_e32 v230, v230, v242
	v_sub_f32_e32 v231, v231, v242
	v_sub_f32_e32 v232, v232, v242
	v_sub_f32_e32 v233, v233, v242
	v_sub_f32_e32 v234, v234, v242
	v_sub_f32_e32 v235, v235, v242
	v_sub_f32_e32 v236, v236, v242
	v_sub_f32_e32 v237, v237, v242
	v_sub_f32_e32 v238, v238, v242
	v_sub_f32_e32 v239, v239, v242
	v_sub_f32_e32 v240, v240, v242
	v_sub_f32_e32 v241, v241, v242
	s_branch .LBB0_131

; __device__ __forceinline__ void finishSM(f32x16& p0, f32x16& p1, float alpha, float& l_reg, bf16x8& pa0, bf16x8& pa1, bf16x8& pa2, bf16x8& pa3) {
; #pragma unroll
;   for (int r = 0; r < 16; ++r) p1[r] = __builtin_amdgcn_exp2f(p1[r]);
;   float ps = 0;
; #pragma unroll
;   for (int r = 0; r < 16; ++r) ps += p0[r];
; #pragma unroll
;   for (int r = 0; r < 16; ++r) ps += p1[r];
;   { auto rr = __builtin_amdgcn_permlane32_swap(__float_as_uint(ps), __float_as_uint(ps), false, false);
;     ps = __uint_as_float(rr[0]) + __uint_as_float(rr[1]); }
;   l_reg = l_reg * alpha + ps;
;     ...
;   PK4(p0, 0, pa0); PK4(p0, 8, pa1); PK4(p1, 0, pa2); PK4(p1, 8, pa3);
;     ...
; }
; template <int BUFOFF>
; __device__ __forceinline__ void qkt_diff(f32x16& p0, f32x16& p1, const int* ka, const bf16x8* qr) {
;   typedef __attribute__((address_space(3))) const bf16x8* lp;
;   p0 = f32x16{}; p1 = f32x16{};
; #pragma unroll
;   for (int d0 = 0; d0 < 4; ++d0) {
;     const int a = ka[d0] + BUFOFF;
;     const bf16x8 b0 = *(lp)(a), b1 = *(lp)(a + 8192);
;     p0 = __builtin_amdgcn_mfma_f32_32x32x16_bf16(b0, qr[d0], p0, 0, 0, 0);
;     p1 = __builtin_amdgcn_mfma_f32_32x32x16_bf16(b1, qr[d0], p1, 0, 0, 0);
;   }
; }
.LBB0_131:
	v_exp_f32_e32 v125, v64
	v_exp_f32_e32 v126, v65
	v_exp_f32_e32 v127, v66
	v_exp_f32_e32 v128, v67
	v_exp_f32_e32 v129, v68
	v_exp_f32_e32 v143, v69
	v_exp_f32_e32 v144, v70
	v_exp_f32_e32 v145, v71
	v_exp_f32_e32 v146, v72
	v_exp_f32_e32 v147, v73
	v_exp_f32_e32 v148, v74
	v_exp_f32_e32 v149, v75
	v_exp_f32_e32 v150, v76
	v_exp_f32_e32 v151, v80
	v_exp_f32_e32 v152, v81
	v_exp_f32_e32 v153, v82
	v_exp_f32_e32 v154, v83
	v_exp_f32_e32 v155, v84
	v_exp_f32_e32 v156, v85
	v_exp_f32_e32 v158, v86
	v_exp_f32_e32 v159, v87
	v_exp_f32_e32 v162, v88
	v_exp_f32_e32 v167, v89
	v_exp_f32_e32 v169, v90
	v_exp_f32_e32 v170, v91
	v_exp_f32_e32 v171, v92
	v_exp_f32_e32 v172, v93
	v_exp_f32_e32 v173, v94
	v_exp_f32_e32 v188, v95
	v_exp_f32_e32 v189, v77
	v_exp_f32_e32 v190, v78
	v_exp_f32_e32 v124, v79
	ds_read_b128 v[64:67], v138
	ds_read_b128 v[68:71], v138 offset:8192
	ds_read_b128 v[112:115], v141
	ds_read_b128 v[120:123], v141 offset:8192
	v_mov_b32_e32 v191, v125
	s_waitcnt lgkmcnt(0)
	v_mfma_f32_32x32x16_bf16 v[80:95], v[64:67], v[108:111], v[226:241]
	v_mfma_f32_32x32x16_bf16 v[64:79], v[68:71], v[108:111], v[226:241]
	v_mov_b32_e32 v192, v124
	v_mfma_f32_32x32x16_bf16 v[80:95], v[112:115], v[104:107], v[80:95]
	v_mfma_f32_32x32x16_bf16 v[64:79], v[120:123], v[104:107], v[64:79]
	ds_read_b128 v[112:115], v140
	ds_read_b128 v[120:123], v140 offset:8192
	s_waitcnt lgkmcnt(0)
	v_mfma_f32_32x32x16_bf16 v[80:95], v[112:115], v[100:103], v[80:95]
	v_mfma_f32_32x32x16_bf16 v[64:79], v[120:123], v[100:103], v[64:79]
	ds_read_b128 v[112:115], v139
	ds_read_b128 v[120:123], v139 offset:8192
	s_waitcnt lgkmcnt(0)
	v_mfma_f32_32x32x16_bf16 v[80:95], v[112:115], v[96:99], v[80:95]
	v_add_f32_e32 v112, v162, v151
	v_add_f32_e32 v243, v167, v152
	v_add_f32_e32 v244, v169, v153
	v_add_f32_e32 v245, v170, v154
	v_add_f32_e32 v246, v171, v155
	v_add_f32_e32 v247, v172, v156
	v_add_f32_e32 v251, v173, v158
	v_add_f32_e32 v252, v188, v159
	v_add_f32_e32 v112, v191, v112
	v_add_f32_e32 v243, v126, v243
	v_add_f32_e32 v244, v127, v244
	v_add_f32_e32 v245, v128, v245
	v_add_f32_e32 v246, v129, v246
	v_add_f32_e32 v247, v143, v247
	v_add_f32_e32 v251, v144, v251
	v_add_f32_e32 v252, v145, v252
	v_add_f32_e32 v112, v146, v112
	v_add_f32_e32 v243, v147, v243
	v_mfma_f32_32x32x16_bf16 v[64:79], v[120:123], v[96:99], v[64:79]
	v_add_f32_e32 v244, v148, v244
	v_add_f32_e32 v245, v149, v245
	v_add_f32_e32 v246, v150, v246
	v_add_f32_e32 v247, v189, v247
	v_add_f32_e32 v251, v190, v251
	v_add_f32_e32 v252, v192, v252
	v_add_f32_e32 v112, v112, v243
	v_add_f32_e32 v244, v244, v245
	v_add_f32_e32 v246, v246, v247
	v_add_f32_e32 v251, v251, v252
	v_add_f32_e32 v112, v112, v244
	v_add_f32_e32 v246, v246, v251
	v_add_f32_e32 v120, v112, v246
	v_mov_b32_e32 v121, v120
	v_cvt_pk_bf16_f32 v112, v151, v152
	v_cvt_pk_bf16_f32 v113, v153, v154
	v_cvt_pk_bf16_f32 v114, v155, v156
	v_cvt_pk_bf16_f32 v115, v158, v159
	s_nop 1
	v_permlane32_swap_b32_e32 v120, v121
	v_cvt_pk_bf16_f32 v122, v162, v167
	v_cvt_pk_bf16_f32 v123, v169, v170
	v_cvt_pk_bf16_f32 v124, v171, v172
	v_cvt_pk_bf16_f32 v125, v173, v188
	v_cvt_pk_bf16_f32 v126, v191, v126
	v_cvt_pk_bf16_f32 v127, v127, v128
	v_cvt_pk_bf16_f32 v128, v129, v143
	v_cvt_pk_bf16_f32 v129, v144, v145
	v_cvt_pk_bf16_f32 v144, v146, v147
	v_cvt_pk_bf16_f32 v145, v148, v149
	v_cvt_pk_bf16_f32 v146, v150, v189
	v_cvt_pk_bf16_f32 v147, v190, v192
	s_nop 0
	s_add_u32 s4, s14, 0x20000
	s_addc_u32 s5, s15, 0
	s_add_u32 s56, s14, 0x2020000
	s_mov_b32 m0, s16
	s_addc_u32 s57, s15, 0
	s_add_i32 s55, s42, s55
	s_nop 0
	global_load_lds_dwordx4 v134, s[4:5]
	s_mov_b32 m0, s17
	s_nop 0
	global_load_lds_dwordx4 v135, s[4:5]
	s_mov_b32 m0, s55
	s_nop 0
	global_load_lds_dwordx4 v136, s[56:57]
	s_add_i32 m0, s55, 0x2000
	s_nop 0
	global_load_lds_dwordx4 v137, s[56:57]
	v_lshl_add_u32 v143, s54, 14, v133
	ds_read_b64_tr_b16 v[148:149], v143 offset:0
	ds_read_b64_tr_b16 v[150:151], v143 offset:0x800
	ds_read_b64_tr_b16 v[152:153], v143 offset:0x1000
	ds_read_b64_tr_b16 v[154:155], v143 offset:0x1800
	ds_read_b64_tr_b16 v[170:171], v143 offset:0x2000
	ds_read_b64_tr_b16 v[172:173], v143 offset:0x2800
	ds_read_b64_tr_b16 v[188:189], v143 offset:0x3000
	ds_read_b64_tr_b16 v[190:191], v143 offset:0x3800
	s_waitcnt lgkmcnt(0)
	s_nop 0
	v_mfma_f32_32x32x16_bf16 v[32:47], v[148:151], v[112:115], v[32:47]
	ds_read_b64_tr_b16 v[148:149], v143 offset:0x200
	ds_read_b64_tr_b16 v[150:151], v143 offset:0xa00
	v_mfma_f32_32x32x16_bf16 v[32:47], v[152:155], v[122:125], v[32:47]
	ds_read_b64_tr_b16 v[152:153], v143 offset:0x1200
	ds_read_b64_tr_b16 v[154:155], v143 offset:0x1a00
	v_mfma_f32_32x32x16_bf16 v[32:47], v[170:173], v[126:129], v[32:47]
	ds_read_b64_tr_b16 v[170:171], v143 offset:0x2200
	ds_read_b64_tr_b16 v[172:173], v143 offset:0x2a00
	v_mfma_f32_32x32x16_bf16 v[32:47], v[188:191], v[144:147], v[32:47]
	ds_read_b64_tr_b16 v[188:189], v143 offset:0x3200
	ds_read_b64_tr_b16 v[190:191], v143 offset:0x3a00
	s_waitcnt lgkmcnt(0)
	v_mfma_f32_32x32x16_bf16 v[48:63], v[148:151], v[112:115], v[48:63]
	ds_read_b64_tr_b16 v[148:149], v143 offset:0x400
	ds_read_b64_tr_b16 v[150:151], v143 offset:0xc00
	v_mfma_f32_32x32x16_bf16 v[48:63], v[152:155], v[122:125], v[48:63]
	ds_read_b64_tr_b16 v[152:153], v143 offset:0x1400
	ds_read_b64_tr_b16 v[154:155], v143 offset:0x1c00
	v_mfma_f32_32x32x16_bf16 v[48:63], v[170:173], v[126:129], v[48:63]
	ds_read_b64_tr_b16 v[170:171], v143 offset:0x2400
	ds_read_b64_tr_b16 v[172:173], v143 offset:0x2c00
	v_mfma_f32_32x32x16_bf16 v[48:63], v[188:191], v[144:147], v[48:63]
	ds_read_b64_tr_b16 v[188:189], v143 offset:0x3400
	ds_read_b64_tr_b16 v[190:191], v143 offset:0x3c00
	s_waitcnt lgkmcnt(0)
; #define SBAR() __builtin_amdgcn_sched_barrier(0)
; template <int MLA>
; __device__ __forceinline__ void partialSM(f32x16& p0, f32x16& p1, float& m_reg, float& mn, float& alpha) {
;     ...
;   float pmax = p0[0];
; #pragma unroll
;   for (int r = 1; r < 16; ++r) pmax = fmaxf(pmax, p0[r]);
; #pragma unroll
;   for (int r = 0; r < 16; ++r) pmax = fmaxf(pmax, p1[r]);
;   { auto rr = __builtin_amdgcn_permlane32_swap(__float_as_uint(pmax), __float_as_uint(pmax), false, false);
;     pmax = fmaxf(__uint_as_float(rr[0]), __uint_as_float(rr[1])); }
;   if (__builtin_expect(__all(pmax - m_reg <= THR / SCALE), 1)) { mn = m_reg; alpha = 1.f; }
;   else { mn = fmaxf(m_reg, pmax); alpha = __builtin_amdgcn_exp2f((m_reg - mn) * C); m_reg = mn; }
;   float mnC = -mn * C;
; #pragma unroll
;   for (int r = 0; r < 16; ++r) p0[r] = fmaf(p0[r], C, mnC);
; #pragma unroll
;   for (int r = 0; r < 16; ++r) p1[r] = fmaf(p1[r], C, mnC);
; template <int D0> __device__ __forceinline__ void pv_one_t(f32x16& od, int vb, bf16x8 pa0, bf16x8 pa1, bf16x8 pa2, bf16x8 pa3) {
;   const s16x4 l0 = tr_read<v_rd_off(D0, 0, 0)>(vb), h0 = tr_read<v_rd_off(D0, 0, 1)>(vb), l1 = tr_read<v_rd_off(D0, 1, 0)>(vb), h1 = tr_read<v_rd_off(D0, 1, 1)>(vb);
;   const s16x4 l2 = tr_read<v_rd_off(D0, 2, 0)>(vb), h2 = tr_read<v_rd_off(D0, 2, 1)>(vb), l3 = tr_read<v_rd_off(D0, 3, 0)>(vb), h3 = tr_read<v_rd_off(D0, 3, 1)>(vb);
;   asm volatile("s_waitcnt lgkmcnt(0)" ::: "memory"); SBAR();
;     ...
;   od = __builtin_amdgcn_mfma_f32_32x32x16_bf16(PK(l0, h0), pa0, od, 0, 0, 0);
;   od = __builtin_amdgcn_mfma_f32_32x32x16_bf16(PK(l1, h1), pa1, od, 0, 0, 0);
;   od = __builtin_amdgcn_mfma_f32_32x32x16_bf16(PK(l2, h2), pa2, od, 0, 0, 0);
;   od = __builtin_amdgcn_mfma_f32_32x32x16_bf16(PK(l3, h3), pa3, od, 0, 0, 0);
;     ...
; }
; __device__ __forceinline__ void pv_d0_t(f32x16* o, int vb, bf16x8 pa0, bf16x8 pa1, bf16x8 pa2, bf16x8 pa3) {
;   pv_one_t<0>(o[0], vb, pa0, pa1, pa2, pa3); pv_one_t<1>(o[1], vb, pa0, pa1, pa2, pa3); pv_one_t<2>(o[2], vb, pa0, pa1, pa2, pa3); pv_one_t<3>(o[3], vb, pa0, pa1, pa2, pa3);
; }
	v_mfma_f32_32x32x16_bf16 v[16:31], v[148:151], v[112:115], v[16:31]
	ds_read_b64_tr_b16 v[148:149], v143 offset:0x600
	ds_read_b64_tr_b16 v[150:151], v143 offset:0xe00
	v_mfma_f32_32x32x16_bf16 v[16:31], v[152:155], v[122:125], v[16:31]
	ds_read_b64_tr_b16 v[152:153], v143 offset:0x1600
	ds_read_b64_tr_b16 v[154:155], v143 offset:0x1e00
	v_mfma_f32_32x32x16_bf16 v[16:31], v[170:173], v[126:129], v[16:31]
	ds_read_b64_tr_b16 v[170:171], v143 offset:0x2600
	ds_read_b64_tr_b16 v[172:173], v143 offset:0x2e00
	v_mfma_f32_32x32x16_bf16 v[16:31], v[188:191], v[144:147], v[16:31]
	ds_read_b64_tr_b16 v[188:189], v143 offset:0x3600
	ds_read_b64_tr_b16 v[190:191], v143 offset:0x3e00
	s_waitcnt lgkmcnt(0)
	v_mfma_f32_32x32x16_bf16 v[0:15], v[148:151], v[112:115], v[0:15]
	v_max_f32_e32 v112, v80, v81
	v_max3_f32 v112, v112, v82, v83
	v_max3_f32 v112, v112, v84, v85
	v_max3_f32 v112, v112, v86, v87
	v_max3_f32 v112, v112, v88, v89
	v_max3_f32 v112, v112, v90, v91
	v_max3_f32 v112, v112, v92, v93
	v_mfma_f32_32x32x16_bf16 v[0:15], v[152:155], v[122:125], v[0:15]
	v_max3_f32 v112, v112, v94, v95
	v_max3_f32 v112, v112, v64, v65
	v_max3_f32 v112, v112, v66, v67
	v_max3_f32 v112, v112, v68, v69
	v_max3_f32 v112, v112, v70, v71
	v_max3_f32 v112, v112, v72, v73
	v_max3_f32 v112, v112, v74, v75
	v_max3_f32 v112, v112, v76, v77
	v_mfma_f32_32x32x16_bf16 v[0:15], v[170:173], v[126:129], v[0:15]
	v_max3_f32 v112, v112, v78, v79
	v_mov_b32_e32 v113, v112
	s_nop 1
	v_permlane32_swap_b32_e32 v112, v113
	v_max_f32_e32 v112, v112, v113
	v_cmp_ge_f32_e32 vcc, s70, v112
	v_mfma_f32_32x32x16_bf16 v[0:15], v[188:191], v[144:147], v[0:15]
	s_cmp_eq_u64 vcc, exec
	s_cselect_b64 s[4:5], -1, 0
	s_waitcnt vmcnt(0) lgkmcnt(0)
	s_barrier
	s_cbranch_scc1 .Lal_c_d2
	v_max_f32_e32 v242, 0, v112
	v_exp_f32_e64 v112, -v242
	s_nop 0
	v_pk_mul_f32 v[46:47], v[46:47], v[112:113] op_sel_hi:[1,0]
	v_pk_mul_f32 v[44:45], v[44:45], v[112:113] op_sel_hi:[1,0]
	v_pk_mul_f32 v[42:43], v[42:43], v[112:113] op_sel_hi:[1,0]
	v_pk_mul_f32 v[40:41], v[40:41], v[112:113] op_sel_hi:[1,0]
	v_pk_mul_f32 v[38:39], v[38:39], v[112:113] op_sel_hi:[1,0]
	v_pk_mul_f32 v[36:37], v[36:37], v[112:113] op_sel_hi:[1,0]
	v_pk_mul_f32 v[34:35], v[34:35], v[112:113] op_sel_hi:[1,0]
	v_pk_mul_f32 v[32:33], v[32:33], v[112:113] op_sel_hi:[1,0]
	v_pk_mul_f32 v[62:63], v[62:63], v[112:113] op_sel_hi:[1,0]
	v_pk_mul_f32 v[60:61], v[60:61], v[112:113] op_sel_hi:[1,0]
	v_pk_mul_f32 v[58:59], v[58:59], v[112:113] op_sel_hi:[1,0]
	v_pk_mul_f32 v[56:57], v[56:57], v[112:113] op_sel_hi:[1,0]
	v_pk_mul_f32 v[54:55], v[54:55], v[112:113] op_sel_hi:[1,0]
	v_pk_mul_f32 v[52:53], v[52:53], v[112:113] op_sel_hi:[1,0]
	v_pk_mul_f32 v[50:51], v[50:51], v[112:113] op_sel_hi:[1,0]
	v_pk_mul_f32 v[48:49], v[48:49], v[112:113] op_sel_hi:[1,0]
	v_pk_mul_f32 v[30:31], v[30:31], v[112:113] op_sel_hi:[1,0]
	v_pk_mul_f32 v[28:29], v[28:29], v[112:113] op_sel_hi:[1,0]
	v_pk_mul_f32 v[26:27], v[26:27], v[112:113] op_sel_hi:[1,0]
	v_pk_mul_f32 v[24:25], v[24:25], v[112:113] op_sel_hi:[1,0]
	v_pk_mul_f32 v[22:23], v[22:23], v[112:113] op_sel_hi:[1,0]
	v_pk_mul_f32 v[20:21], v[20:21], v[112:113] op_sel_hi:[1,0]
	v_pk_mul_f32 v[18:19], v[18:19], v[112:113] op_sel_hi:[1,0]
	v_pk_mul_f32 v[16:17], v[16:17], v[112:113] op_sel_hi:[1,0]
	v_pk_mul_f32 v[14:15], v[14:15], v[112:113] op_sel_hi:[1,0]
	v_pk_mul_f32 v[12:13], v[12:13], v[112:113] op_sel_hi:[1,0]
	v_pk_mul_f32 v[10:11], v[10:11], v[112:113] op_sel_hi:[1,0]
	v_pk_mul_f32 v[8:9], v[8:9], v[112:113] op_sel_hi:[1,0]
	v_pk_mul_f32 v[6:7], v[6:7], v[112:113] op_sel_hi:[1,0]
	v_pk_mul_f32 v[4:5], v[4:5], v[112:113] op_sel_hi:[1,0]
	v_pk_mul_f32 v[2:3], v[2:3], v[112:113] op_sel_hi:[1,0]
	v_pk_mul_f32 v[0:1], v[0:1], v[112:113] op_sel_hi:[1,0]
	v_sub_f32_e32 v80, v80, v242
	v_sub_f32_e32 v81, v81, v242
	v_sub_f32_e32 v82, v82, v242
	v_sub_f32_e32 v83, v83, v242
	v_sub_f32_e32 v84, v84, v242
	v_sub_f32_e32 v85, v85, v242
	v_sub_f32_e32 v86, v86, v242
	v_sub_f32_e32 v87, v87, v242
	v_sub_f32_e32 v88, v88, v242
	v_sub_f32_e32 v89, v89, v242
	v_sub_f32_e32 v90, v90, v242
	v_sub_f32_e32 v91, v91, v242
	v_sub_f32_e32 v92, v92, v242
	v_sub_f32_e32 v93, v93, v242
	v_sub_f32_e32 v94, v94, v242
	v_sub_f32_e32 v95, v95, v242
	v_sub_f32_e32 v64, v64, v242
	v_sub_f32_e32 v65, v65, v242
	v_sub_f32_e32 v66, v66, v242
	v_sub_f32_e32 v67, v67, v242
	v_sub_f32_e32 v68, v68, v242
	v_sub_f32_e32 v69, v69, v242
	v_sub_f32_e32 v70, v70, v242
	v_sub_f32_e32 v71, v71, v242
	v_sub_f32_e32 v72, v72, v242
	v_sub_f32_e32 v73, v73, v242
	v_sub_f32_e32 v74, v74, v242
	v_sub_f32_e32 v75, v75, v242
	v_sub_f32_e32 v76, v76, v242
	v_sub_f32_e32 v77, v77, v242
	v_sub_f32_e32 v78, v78, v242
	v_sub_f32_e32 v79, v79, v242
	v_sub_f32_e32 v226, v226, v242
	v_sub_f32_e32 v227, v227, v242
	v_sub_f32_e32 v228, v228, v242
	v_sub_f32_e32 v229, v229, v242
	v_sub_f32_e32 v230, v230, v242
	v_sub_f32_e32 v231, v231, v242
	v_sub_f32_e32 v232, v232, v242
	v_sub_f32_e32 v233, v233, v242
	v_sub_f32_e32 v234, v234, v242
	v_sub_f32_e32 v235, v235, v242
	v_sub_f32_e32 v236, v236, v242
	v_sub_f32_e32 v237, v237, v242
	v_sub_f32_e32 v238, v238, v242
	v_sub_f32_e32 v239, v239, v242
	v_sub_f32_e32 v240, v240, v242
	v_sub_f32_e32 v241, v241, v242
	s_branch .LBB0_133

; __global__ __launch_bounds__(512, 2) void mega(Params p) {
	.amdhsa_kernel _Z4mega6Params
		.amdhsa_group_segment_fixed_size 0
		.amdhsa_private_segment_fixed_size 0
		.amdhsa_kernarg_size 432
		.amdhsa_user_sgpr_count 2
		.amdhsa_user_sgpr_dispatch_ptr 0
		.amdhsa_user_sgpr_queue_ptr 0
		.amdhsa_user_sgpr_kernarg_segment_ptr 1
		.amdhsa_user_sgpr_dispatch_id 0
		.amdhsa_user_sgpr_kernarg_preload_length 0
		.amdhsa_user_sgpr_kernarg_preload_offset 0
		.amdhsa_user_sgpr_private_segment_size 0
		.amdhsa_uses_dynamic_stack 0
		.amdhsa_enable_private_segment 0
		.amdhsa_system_sgpr_workgroup_id_x 1
		.amdhsa_system_sgpr_workgroup_id_y 0
		.amdhsa_system_sgpr_workgroup_id_z 0
		.amdhsa_system_sgpr_workgroup_info 0
		.amdhsa_system_vgpr_workitem_id 2
		.amdhsa_next_free_vgpr 256
		.amdhsa_next_free_sgpr 102
		.amdhsa_accum_offset 256
		.amdhsa_reserve_vcc 1
		.amdhsa_float_round_mode_32 0
		.amdhsa_float_round_mode_16_64 0
		.amdhsa_float_denorm_mode_32 3
		.amdhsa_float_denorm_mode_16_64 3
		.amdhsa_dx10_clamp 1
		.amdhsa_ieee_mode 1
		.amdhsa_fp16_overflow 0
		.amdhsa_tg_split 0
		.amdhsa_exception_fp_ieee_invalid_op 0
		.amdhsa_exception_fp_denorm_src 0
		.amdhsa_exception_fp_ieee_div_zero 0
		.amdhsa_exception_fp_ieee_overflow 0
		.amdhsa_exception_fp_ieee_underflow 0
		.amdhsa_exception_fp_ieee_inexact 0
		.amdhsa_exception_int_div_zero 0
	.end_amdhsa_kernel

; __global__ __launch_bounds__(512, 2) void mega(Params p) {
amdhsa.kernels:
  - .agpr_count:     0
    .args:
      - .offset:         0
        .size:           176
        .value_kind:     by_value
      - .offset:         176
        .size:           4
        .value_kind:     hidden_block_count_x
      - .offset:         180
        .size:           4
        .value_kind:     hidden_block_count_y
      - .offset:         184
        .size:           4
        .value_kind:     hidden_block_count_z
      - .offset:         188
        .size:           2
        .value_kind:     hidden_group_size_x
      - .offset:         190
        .size:           2
        .value_kind:     hidden_group_size_y
      - .offset:         192
        .size:           2
        .value_kind:     hidden_group_size_z
      - .offset:         194
        .size:           2
        .value_kind:     hidden_remainder_x
      - .offset:         196
        .size:           2
        .value_kind:     hidden_remainder_y
      - .offset:         198
        .size:           2
        .value_kind:     hidden_remainder_z
      - .offset:         216
        .size:           8
        .value_kind:     hidden_global_offset_x
      - .offset:         224
        .size:           8
        .value_kind:     hidden_global_offset_y
      - .offset:         232
        .size:           8
        .value_kind:     hidden_global_offset_z
      - .offset:         240
        .size:           2
        .value_kind:     hidden_grid_dims
      - .offset:         264
        .size:           8
        .value_kind:     hidden_multigrid_sync_arg
      - .offset:         296
        .size:           4
        .value_kind:     hidden_dynamic_lds_size
    .group_segment_fixed_size: 0
    .kernarg_segment_align: 8
    .kernarg_segment_size: 432
    .language:       OpenCL C
    .language_version:
      - 2
      - 0
    .max_flat_workgroup_size: 512
    .name:           _Z4mega6Params
    .private_segment_fixed_size: 0
    .sgpr_count:     108
    .sgpr_spill_count: 182
    .symbol:         _Z4mega6Params.kd
    .uniform_work_group_size: 1
    .uses_dynamic_stack: false
    .vgpr_count:     256
    .vgpr_spill_count: 0
    .wavefront_size: 64
